# attention: cross-half row-max via v_permlane32_swap instead of ds_bpermute (no LDS round trip on the softmax critical path)
# speedup vs baseline: 1.0795x; 1.0177x over previous
.LBB0_845:
	v_max_f32_e32 v152, v49, v49
	v_max_f32_e32 v153, v48, v48
	v_max_f32_e32 v152, v153, v152
	v_max3_f32 v153, v50, v51, v65
	v_max3_f32 v152, v152, v64, v66
	v_max3_f32 v152, v152, v67, v52
	v_max3_f32 v153, v153, v54, v55
	v_max3_f32 v152, v152, v53, v68
	v_max3_f32 v153, v153, v70, v71
	v_max3_f32 v152, v152, v69, v56
	v_max3_f32 v153, v153, v58, v59
	v_max3_f32 v152, v152, v57, v72
	v_max3_f32 v153, v153, v74, v75
	v_max3_f32 v152, v152, v73, v60
	v_max3_f32 v153, v153, v62, v63
	v_max3_f32 v152, v152, v61, v76
	v_max3_f32 v153, v153, v78, v79
	v_max3_f32 v152, v152, v77, v153
	s_cmp_eq_u32 s73, 0
	v_mov_b32_e32 v153, v152
	v_mov_b32_e32 v154, v152
	s_nop 1
	v_permlane32_swap_b32_e32 v153, v154
	v_max_f32_e32 v205, v153, v154
	s_cbranch_scc1 .LBB0_848
	v_cmp_lt_f32_e32 vcc, s90, v205
	s_cbranch_vccz .LBB0_849
	v_max_f32_e32 v152, v205, v205
	v_max_f32_e32 v205, 0, v152

.LBB0_863:
	v_max_f32_e32 v152, v97, v97
	v_max_f32_e32 v153, v96, v96
	v_max_f32_e32 v152, v153, v152
	v_max3_f32 v153, v98, v99, v113
	v_max3_f32 v152, v152, v112, v114
	v_max3_f32 v152, v152, v115, v100
	v_max3_f32 v153, v153, v102, v103
	v_max3_f32 v152, v152, v101, v116
	v_max3_f32 v153, v153, v118, v119
	v_max3_f32 v152, v152, v117, v104
	v_max3_f32 v153, v153, v106, v107
	v_max3_f32 v152, v152, v105, v120
	v_max3_f32 v153, v153, v122, v123
	v_max3_f32 v152, v152, v121, v108
	v_max3_f32 v153, v153, v110, v111
	v_max3_f32 v152, v152, v109, v124
	v_max3_f32 v153, v153, v126, v127
	v_max3_f32 v152, v152, v125, v153
	v_mov_b32_e32 v153, v152
	v_mov_b32_e32 v154, v152
	s_nop 1
	v_permlane32_swap_b32_e32 v153, v154
	v_max_f32_e32 v152, v153, v154
	v_cmp_lt_f32_e32 vcc, s90, v152
	s_cbranch_vccz .LBB0_869
	v_max_f32_e32 v81, v152, v152
	v_max_f32_e32 v81, 0, v81
	v_exp_f32_e64 v231, -v81
	s_and_saveexec_b64 s[2:3], s[10:11]
	v_exp_f32_e64 v82, -v81
	ds_write_b32 v203, v82 offset:61440
	s_or_b64 exec, exec, s[2:3]
	v_mul_f32_e32 v230, v230, v231
	v_mul_f32_e32 v252, v252, v231
	s_waitcnt lgkmcnt(0)
	ds_read_b128 v[152:155], v204 offset:61440
	ds_read_b128 v[156:159], v204 offset:61472
	ds_read_b128 v[160:163], v204 offset:61504
	ds_read_b128 v[164:167], v204 offset:61536
	s_andn2_b64 vcc, exec, s[16:17]
	s_cbranch_vccnz .LBB0_868
	v_sub_f32_e32 v63, v63, v81
	v_sub_f32_e32 v62, v62, v81
	v_sub_f32_e32 v61, v61, v81
	v_sub_f32_e32 v60, v60, v81
	v_sub_f32_e32 v59, v59, v81
	v_sub_f32_e32 v58, v58, v81
	v_sub_f32_e32 v57, v57, v81
	v_sub_f32_e32 v56, v56, v81
	v_sub_f32_e32 v55, v55, v81
	v_sub_f32_e32 v54, v54, v81
	v_sub_f32_e32 v53, v53, v81
	v_sub_f32_e32 v52, v52, v81
	v_sub_f32_e32 v51, v51, v81
	v_sub_f32_e32 v50, v50, v81
	v_sub_f32_e32 v49, v49, v81
	v_sub_f32_e32 v48, v48, v81
	v_sub_f32_e32 v79, v79, v81
	v_sub_f32_e32 v78, v78, v81
	v_sub_f32_e32 v77, v77, v81
	v_sub_f32_e32 v76, v76, v81
	v_sub_f32_e32 v75, v75, v81
	v_sub_f32_e32 v74, v74, v81
	v_sub_f32_e32 v73, v73, v81
	v_sub_f32_e32 v72, v72, v81
	v_sub_f32_e32 v71, v71, v81
	v_sub_f32_e32 v70, v70, v81
	v_sub_f32_e32 v69, v69, v81
	v_sub_f32_e32 v68, v68, v81
	v_sub_f32_e32 v67, v67, v81
	v_sub_f32_e32 v66, v66, v81
	v_sub_f32_e32 v65, v65, v81
	v_sub_f32_e32 v64, v64, v81
